# layer-0 conversion tiles of the 16 blocks that still have a context attention item handed to blocks 16..207 (one extra tile each)
# speedup vs baseline: 1.2806x; 1.0011x over previous
; __device__ __forceinline__ int tid_() { int t = threadIdx.x; asm volatile("" : "+v"(t)); return t; }
; __device__ __forceinline__ void convT_tile(const float* __restrict__ src, int lds, int k0, int c0, u16* __restrict__ dst, int Kd,
;                                            int rbase, int mode, int which, unsigned char* smem, const float* __restrict__ kscale = nullptr) {
;   float* tile = (float*)smem;
;   const int t = tid_();
;   float4 v4[4];
; #pragma unroll
;   for (int i = 0; i < 4; ++i) {
;     const f32x4 w_ = __builtin_nontemporal_load((const f32x4*)(src + (size_t)(k0 + i * 16 + (t >> 4)) * lds + c0 + (t & 15) * 4));
;     v4[i] = make_float4(w_[0], w_[1], w_[2], w_[3]);
;   }
; #pragma unroll
;   for (int i = 0; i < 4; ++i) {
;     const int kk = i * 16 + (t >> 4), cc = (t & 15) * 4;
; __device__ __forceinline__ void conv_item(const Params& p, int it, unsigned char* smem) {
;     ...
;   if (r < 4096) {
;     const int which = r >> 11, r2 = r & 2047, e = r2 >> 7, r3 = r2 & 127, ct = r3 >> 4, kt = r3 & 15;
;     const float* src = (which ? p.w_up : p.w_gate) + (size_t)(l * 16 + e) * 1024 * 512;
;     convT_tile(src, 512, kt * 64, ct * 64, p.WguT + (size_t)(l * 16 + e) * 1024 * 1024, 1024, 0, 1, which, smem);
;     return;
.Lcv_entry:
	s_load_dwordx2 s[52:53], s[4:5], 0x90
	s_load_dwordx2 s[54:55], s[4:5], 0x98
	s_load_dwordx2 s[56:57], s[4:5], 0xa0
	s_load_dwordx2 s[98:99], s[4:5], 0xe0
	s_load_dwordx2 s[100:101], s[4:5], 0xe8
	v_lshrrev_b32_e32 v98, 4, v187
	v_add_u32_e32 v99, 16, v98
	v_add_u32_e32 v100, 32, v98
	v_add_u32_e32 v101, 48, v98
	v_and_b32_e32 v122, 15, v187
	v_lshlrev_b32_e32 v102, 4, v122
	v_lshrrev_b32_e32 v123, 3, v187
	v_and_b32_e32 v122, 7, v187
	v_lshrrev_b32_e32 v36, 4, v123
	v_and_b32_e32 v37, 15, v123
	v_lshl_add_u32 v36, v36, 5, v37
	v_lshlrev_b32_e32 v36, 11, v36
	v_lshl_add_u32 v103, v122, 4, v36
	v_lshlrev_b32_e32 v36, 10, v123
	v_lshl_add_u32 v105, v122, 4, v36
	v_add_u32_e32 v123, 32, v123
	v_lshrrev_b32_e32 v36, 4, v123
	v_and_b32_e32 v37, 15, v123
	v_lshl_add_u32 v36, v36, 5, v37
	v_lshlrev_b32_e32 v36, 11, v36
	v_lshl_add_u32 v104, v122, 4, v36
	v_lshlrev_b32_e32 v36, 10, v123
	v_lshl_add_u32 v106, v122, 4, v36
	v_subrev_u32_e32 v123, 32, v123
	v_mul_u32_u24_e32 v36, 0x820, v122
	v_lshl_add_u32 v115, v123, 2, v36
	v_mul_u32_u24_e32 v37, 0x104, v98
	v_add_u32_e32 v107, v37, v102
	v_add_u32_e32 v111, 0x4100, v107
	v_mul_u32_u24_e32 v37, 0x104, v99
	v_add_u32_e32 v108, v37, v102
	v_add_u32_e32 v112, 0x4100, v108
	v_mul_u32_u24_e32 v37, 0x104, v100
	v_add_u32_e32 v109, v37, v102
	v_add_u32_e32 v113, 0x4100, v109
	v_mul_u32_u24_e32 v37, 0x104, v101
	v_add_u32_e32 v110, v37, v102
	v_add_u32_e32 v114, 0x4100, v110
	s_mov_b32 s34, -1
	s_cmp_lg_u32 s36, 0
	s_cbranch_scc1 .Lcv_noex
	s_cmp_lt_u32 s2, 16
	s_cbranch_scc1 .Lcv_exit
	s_cmp_lt_u32 s2, 208
	s_cbranch_scc0 .Lcv_noex
	s_sub_i32 s0, s2, 16
	s_and_b32 s34, s0, 15
	s_lshr_b32 s0, s0, 4
	s_lshl_b32 s0, s0, 9
	s_add_i32 s34, s34, s0
.Lcv_noex:
	s_waitcnt lgkmcnt(0)
	s_barrier
	s_add_i32 s59, s2, 0x0
	s_cmp_lt_u32 s59, 0x1000
	s_cbranch_scc0 .Lcv_sd0
	s_lshr_b32 s60, s59, 11
	s_bfe_u32 s71, s59, 0x40007
	s_bfe_u32 s35, s59, 0x30004
	s_and_b32 s51, s59, 15
	s_lshl_b32 s0, s36, 4
	s_add_i32 s71, s71, s0
	s_lshl_b32 s71, s71, 21
	s_lshl_b32 s0, s51, 17
	s_add_i32 s71, s71, s0
	s_lshl_b32 s0, s35, 8
	s_add_i32 s71, s71, s0
	s_cmp_eq_u32 s60, 0
	s_cselect_b32 s88, s52, s54
	s_cselect_b32 s89, s53, s55
	s_add_u32 s88, s88, s71
	s_addc_u32 s89, s89, 0
	s_mov_b32 s94, 11
	s_branch .Lcv_se0

; __device__ __forceinline__ u16 f2bf(float f) { return (u16)(pack2(f, 0.f) & 0xffffu); }
; __device__ __forceinline__ void convT_tile(const float* __restrict__ src, int lds, int k0, int c0, u16* __restrict__ dst, int Kd,
;                                            int rbase, int mode, int which, unsigned char* smem, const float* __restrict__ kscale = nullptr) {
;     ...
;   __syncthreads();
; #pragma unroll
;   for (int i = 0; i < 16; ++i) {
;     const int cc = i * 4 + (t >> 6), kk = t & 63;
;     int row;
;     if (mode == 0) row = rbase + cc;
;     else { const int f = c0 + cc; row = (((f >> 4) * 2 + which) << 4) + (f & 15); }
;     dst[(size_t)row * Kd + k0 + kk] = f2bf(tile[kk * 65 + cc]);
;   }
; __device__ __forceinline__ void conv_item(const Params& p, int it, unsigned char* smem) {
;     ...
;   if (r < 4096) {
;     const int which = r >> 11, r2 = r & 2047, e = r2 >> 7, r3 = r2 & 127, ct = r3 >> 4, kt = r3 & 15;
;     const float* src = (which ? p.w_up : p.w_gate) + (size_t)(l * 16 + e) * 1024 * 512;
;     convT_tile(src, 512, kt * 64, ct * 64, p.WguT + (size_t)(l * 16 + e) * 1024 * 1024, 1024, 0, 1, which, smem);
;     return;
.Lcv_de10:
	s_waitcnt vmcnt(6)
	ds_write2_b32 v107, v132, v133 offset1:1
	ds_write2_b32 v107, v134, v135 offset0:2 offset1:3
	ds_write2_b32 v108, v136, v137 offset1:1
	ds_write2_b32 v108, v138, v139 offset0:2 offset1:3
	ds_write2_b32 v109, v140, v141 offset1:1
	ds_write2_b32 v109, v142, v143 offset0:2 offset1:3
	ds_write2_b32 v110, v144, v145 offset1:1
	ds_write2_b32 v110, v146, v147 offset0:2 offset1:3
	s_waitcnt lgkmcnt(0)
	s_barrier
	ds_read_b32 v72, v115 offset:0
	ds_read_b32 v73, v115 offset:260
	ds_read_b32 v74, v115 offset:520
	ds_read_b32 v75, v115 offset:780
	ds_read_b32 v76, v115 offset:1040
	ds_read_b32 v77, v115 offset:1300
	ds_read_b32 v78, v115 offset:1560
	ds_read_b32 v79, v115 offset:1820
	ds_read_b32 v26, v115 offset:128
	ds_read_b32 v27, v115 offset:388
	ds_read_b32 v28, v115 offset:648
	ds_read_b32 v29, v115 offset:908
	ds_read_b32 v30, v115 offset:1168
	ds_read_b32 v31, v115 offset:1428
	ds_read_b32 v32, v115 offset:1688
	ds_read_b32 v33, v115 offset:1948
	s_waitcnt lgkmcnt(8)
	v_cvt_pk_bf16_f32 v124, v72, v73
	v_cvt_pk_bf16_f32 v125, v74, v75
	v_cvt_pk_bf16_f32 v126, v76, v77
	v_cvt_pk_bf16_f32 v127, v78, v79
	global_store_dwordx4 v120, v[124:127], s[0:1]
	s_waitcnt lgkmcnt(0)
	v_cvt_pk_bf16_f32 v128, v26, v27
	v_cvt_pk_bf16_f32 v129, v28, v29
	v_cvt_pk_bf16_f32 v130, v30, v31
	v_cvt_pk_bf16_f32 v131, v32, v33
	global_store_dwordx4 v121, v[128:131], s[0:1]
	s_cmp_lt_i32 s34, 0
	s_cbranch_scc1 .Lcv_nol12
	s_mov_b32 s59, s34
	s_cmp_lt_u32 s59, 0x1000
	s_cbranch_scc0 .Lcv_sd12
	s_lshr_b32 s60, s59, 11
	s_bfe_u32 s71, s59, 0x40007
	s_bfe_u32 s35, s59, 0x30004
	s_and_b32 s51, s59, 15
	s_lshl_b32 s0, s36, 4
	s_add_i32 s71, s71, s0
	s_lshl_b32 s71, s71, 21
	s_lshl_b32 s0, s51, 17
	s_add_i32 s71, s71, s0
	s_lshl_b32 s0, s35, 8
	s_add_i32 s71, s71, s0
	s_cmp_eq_u32 s60, 0
	s_cselect_b32 s88, s52, s54
	s_cselect_b32 s89, s53, s55
	s_add_u32 s88, s88, s71
	s_addc_u32 s89, s89, 0
	s_mov_b32 s94, 11
	s_branch .Lcv_se12

; __device__ __forceinline__ void conv_item(const Params& p, int it, unsigned char* smem) {
;     ...
;   if (r < 4096) {
;     const int which = r >> 11, r2 = r & 2047, e = r2 >> 7, r3 = r2 & 127, ct = r3 >> 4, kt = r3 & 15;
;     const float* src = (which ? p.w_up : p.w_gate) + (size_t)(l * 16 + e) * 1024 * 512;
;     convT_tile(src, 512, kt * 64, ct * 64, p.WguT + (size_t)(l * 16 + e) * 1024 * 1024, 1024, 0, 1, which, smem);
;     return;
.Lcv_nol12:
	s_add_i32 s59, s2, 0x1600
	s_cmp_lt_u32 s59, 0x1000
	s_cbranch_scc0 .Lcv_dd11
	s_lshr_b32 s60, s59, 11
	s_bfe_u32 s71, s59, 0x40007
	s_bfe_u32 s35, s59, 0x30004
	s_and_b32 s51, s59, 15
	s_lshl_b32 s0, s36, 4
	s_add_i32 s71, s71, s0
	s_lshl_b32 s71, s71, 21
	s_lshl_b32 s35, s35, 7
	s_lshl_b32 s60, s60, 4
	s_add_i32 s35, s35, s60
	s_lshl_b32 s35, s35, 11
	s_add_i32 s71, s71, s35
	s_lshl_b32 s51, s51, 7
	s_add_i32 s71, s71, s51
	s_add_u32 s0, s98, s71
	s_addc_u32 s1, s99, 0
	v_mov_b32_e32 v120, v103
	v_mov_b32_e32 v121, v104
	s_branch .Lcv_de11

; __device__ __forceinline__ void convT_tile(const float* __restrict__ src, int lds, int k0, int c0, u16* __restrict__ dst, int Kd,
;                                            int rbase, int mode, int which, unsigned char* smem, const float* __restrict__ kscale = nullptr) {
;     ...
; #pragma unroll
;   for (int i = 0; i < 4; ++i) {
;     const int kk = i * 16 + (t >> 4), cc = (t & 15) * 4;
;     const float sc = kscale ? kscale[k0 + kk] : 1.f;
;     tile[kk * 65 + cc + 0] = v4[i].x * sc; tile[kk * 65 + cc + 1] = v4[i].y * sc;
;     tile[kk * 65 + cc + 2] = v4[i].z * sc; tile[kk * 65 + cc + 3] = v4[i].w * sc;
;   }
;   __syncthreads();
.Lcv_de11:
	s_cmp_lt_i32 s34, 0
	s_cbranch_scc1 .Lcv_w11
	s_waitcnt vmcnt(6)
	s_branch .Lcv_w11b

; __device__ __forceinline__ u16 f2bf(float f) { return (u16)(pack2(f, 0.f) & 0xffffu); }
; __device__ __forceinline__ void convT_tile(const float* __restrict__ src, int lds, int k0, int c0, u16* __restrict__ dst, int Kd,
;                                            int rbase, int mode, int which, unsigned char* smem, const float* __restrict__ kscale = nullptr) {
;     ...
;   __syncthreads();
; #pragma unroll
;   for (int i = 0; i < 16; ++i) {
;     const int cc = i * 4 + (t >> 6), kk = t & 63;
;     int row;
;     if (mode == 0) row = rbase + cc;
;     else { const int f = c0 + cc; row = (((f >> 4) * 2 + which) << 4) + (f & 15); }
;     dst[(size_t)row * Kd + k0 + kk] = f2bf(tile[kk * 65 + cc]);
;   }
;   __syncthreads();
; }
.Lcv_w11b:
	ds_write2_b32 v111, v148, v149 offset1:1
	ds_write2_b32 v111, v150, v151 offset0:2 offset1:3
	ds_write2_b32 v112, v152, v153 offset1:1
	ds_write2_b32 v112, v154, v155 offset0:2 offset1:3
	ds_write2_b32 v113, v156, v157 offset1:1
	ds_write2_b32 v113, v158, v159 offset0:2 offset1:3
	ds_write2_b32 v114, v160, v161 offset1:1
	ds_write2_b32 v114, v162, v163 offset0:2 offset1:3
	s_waitcnt lgkmcnt(0)
	s_barrier
	ds_read_b32 v72, v115 offset:16640
	ds_read_b32 v73, v115 offset:16900
	ds_read_b32 v74, v115 offset:17160
	ds_read_b32 v75, v115 offset:17420
	ds_read_b32 v76, v115 offset:17680
	ds_read_b32 v77, v115 offset:17940
	ds_read_b32 v78, v115 offset:18200
	ds_read_b32 v79, v115 offset:18460
	ds_read_b32 v26, v115 offset:16768
	ds_read_b32 v27, v115 offset:17028
	ds_read_b32 v28, v115 offset:17288
	ds_read_b32 v29, v115 offset:17548
	ds_read_b32 v30, v115 offset:17808
	ds_read_b32 v31, v115 offset:18068
	ds_read_b32 v32, v115 offset:18328
	ds_read_b32 v33, v115 offset:18588
	s_waitcnt lgkmcnt(8)
	v_cvt_pk_bf16_f32 v124, v72, v73
	v_cvt_pk_bf16_f32 v125, v74, v75
	v_cvt_pk_bf16_f32 v126, v76, v77
	v_cvt_pk_bf16_f32 v127, v78, v79
	global_store_dwordx4 v120, v[124:127], s[0:1]
	s_waitcnt lgkmcnt(0)
	v_cvt_pk_bf16_f32 v128, v26, v27
	v_cvt_pk_bf16_f32 v129, v28, v29
	v_cvt_pk_bf16_f32 v130, v30, v31
	v_cvt_pk_bf16_f32 v131, v32, v33
	global_store_dwordx4 v121, v[128:131], s[0:1]
	s_cmp_lt_i32 s34, 0
	s_cbranch_scc1 .Lcv_exit
	s_mov_b32 s59, s34
	s_cmp_lt_u32 s59, 0x1000
	s_cbranch_scc0 .Lcv_dd12
	s_lshr_b32 s60, s59, 11
	s_bfe_u32 s71, s59, 0x40007
	s_bfe_u32 s35, s59, 0x30004
	s_and_b32 s51, s59, 15
	s_lshl_b32 s0, s36, 4
	s_add_i32 s71, s71, s0
	s_lshl_b32 s71, s71, 21
	s_lshl_b32 s35, s35, 7
	s_lshl_b32 s60, s60, 4
	s_add_i32 s35, s35, s60
	s_lshl_b32 s35, s35, 11
	s_add_i32 s71, s71, s35
	s_lshl_b32 s51, s51, 7
	s_add_i32 s71, s71, s51
	s_add_u32 s0, s98, s71
	s_addc_u32 s1, s99, 0
	v_mov_b32_e32 v120, v103
	v_mov_b32_e32 v121, v104
	s_branch .Lcv_de12

; __device__ __forceinline__ u16 f2bf(float f) { return (u16)(pack2(f, 0.f) & 0xffffu); }
; __device__ __forceinline__ void convT_tile(const float* __restrict__ src, int lds, int k0, int c0, u16* __restrict__ dst, int Kd,
;                                            int rbase, int mode, int which, unsigned char* smem, const float* __restrict__ kscale = nullptr) {
;     ...
;   __syncthreads();
; #pragma unroll
;   for (int i = 0; i < 16; ++i) {
;     const int cc = i * 4 + (t >> 6), kk = t & 63;
;     int row;
;     if (mode == 0) row = rbase + cc;
;     else { const int f = c0 + cc; row = (((f >> 4) * 2 + which) << 4) + (f & 15); }
;     dst[(size_t)row * Kd + k0 + kk] = f2bf(tile[kk * 65 + cc]);
;   }
;   __syncthreads();
; }
.Lcv_de12:
	s_waitcnt vmcnt(2)
	ds_write2_b32 v107, v132, v133 offset1:1
	ds_write2_b32 v107, v134, v135 offset0:2 offset1:3
	ds_write2_b32 v108, v136, v137 offset1:1
	ds_write2_b32 v108, v138, v139 offset0:2 offset1:3
	ds_write2_b32 v109, v140, v141 offset1:1
	ds_write2_b32 v109, v142, v143 offset0:2 offset1:3
	ds_write2_b32 v110, v144, v145 offset1:1
	ds_write2_b32 v110, v146, v147 offset0:2 offset1:3
	s_waitcnt lgkmcnt(0)
	s_barrier
	ds_read_b32 v72, v115 offset:0
	ds_read_b32 v73, v115 offset:260
	ds_read_b32 v74, v115 offset:520
	ds_read_b32 v75, v115 offset:780
	ds_read_b32 v76, v115 offset:1040
	ds_read_b32 v77, v115 offset:1300
	ds_read_b32 v78, v115 offset:1560
	ds_read_b32 v79, v115 offset:1820
	ds_read_b32 v26, v115 offset:128
	ds_read_b32 v27, v115 offset:388
	ds_read_b32 v28, v115 offset:648
	ds_read_b32 v29, v115 offset:908
	ds_read_b32 v30, v115 offset:1168
	ds_read_b32 v31, v115 offset:1428
	ds_read_b32 v32, v115 offset:1688
	ds_read_b32 v33, v115 offset:1948
	s_waitcnt lgkmcnt(8)
	v_cvt_pk_bf16_f32 v124, v72, v73
	v_cvt_pk_bf16_f32 v125, v74, v75
	v_cvt_pk_bf16_f32 v126, v76, v77
	v_cvt_pk_bf16_f32 v127, v78, v79
	global_store_dwordx4 v120, v[124:127], s[0:1]
	s_waitcnt lgkmcnt(0)
	v_cvt_pk_bf16_f32 v128, v26, v27
	v_cvt_pk_bf16_f32 v129, v28, v29
	v_cvt_pk_bf16_f32 v130, v30, v31
	v_cvt_pk_bf16_f32 v131, v32, v33
	global_store_dwordx4 v121, v[128:131], s[0:1]
.Lcv_exit:
	s_waitcnt vmcnt(0) lgkmcnt(0)
	s_barrier
	s_cmp_eq_u32 s32, 0
	s_cbranch_scc1 .Lcv_ret_pre
	s_branch .Lcv_ret_post
